# static s_setprio 1 for waves 4-7 through each GEMM phase (on top of barrier broadcast)
# baseline (speedup 1.0000x reference)
.LBB0_555:
	s_and_b64 vcc, exec, s[0:1]
	s_cbranch_vccz .LBB0_615
	v_readlane_b32 s0, v252, 5
	s_waitcnt vmcnt(0)
	v_mov_b32_e32 v13, v0
	v_readlane_b32 s1, v252, 6
	s_andn2_b64 vcc, exec, s[0:1]
	v_readfirstlane_b32 s6, v13
	s_cbranch_vccnz .LBB0_615
	v_lshlrev_b32_e32 v1, 4, v13
	v_add_u32_e32 v4, 0x2000, v1
	v_ashrrev_i32_e32 v2, 31, v4
	v_lshrrev_b32_e32 v2, 22, v2
	v_add_u32_e32 v2, v4, v2
	v_ashrrev_i32_e32 v2, 10, v2
	v_mul_i32_i24_e32 v5, 0x400, v2
	v_sub_u32_e32 v4, v4, v5
	v_lshrrev_b32_e32 v5, 4, v4
	v_bitop3_b32 v4, v5, v4, 32 bitop3:0x6c
	v_ashrrev_i32_e32 v5, 31, v4
	v_lshrrev_b32_e32 v5, 26, v5
	v_add_u32_e32 v5, v4, v5
	s_waitcnt lgkmcnt(1)
	v_lshlrev_b32_e32 v6, 3, v2
	s_mul_i32 s1, s54, 0x2400000
	v_readlane_b32 s2, v251, 29
	v_ashrrev_i32_e32 v8, 6, v5
	v_and_b32_e32 v6, -16, v6
	s_mul_hi_u32 s0, s54, 0x2400000
	s_add_u32 s12, s2, s1
	v_readlane_b32 s1, v251, 30
	v_add_u32_e32 v6, v8, v6
	s_addc_u32 s13, s1, s0
	s_waitcnt lgkmcnt(0)
	v_and_b32_e32 v7, 3, v8
	s_mov_b32 s0, 0xfffe0
	v_lshrrev_b32_e32 v9, 2, v6
	v_lshlrev_b32_e32 v10, 1, v6
	v_and_b32_e32 v5, 0xc0, v5
	v_and_or_b32 v7, v6, s0, v7
	v_and_b32_e32 v9, 4, v9
	v_and_b32_e32 v10, 24, v10
	v_sub_u32_e32 v4, v4, v5
	v_or3_b32 v7, v7, v9, v10
	v_lshlrev_b32_e32 v9, 5, v2
	v_ashrrev_i16_sdwa v4, v202, sext(v4) dst_sel:DWORD dst_unused:UNUSED_PAD src0_sel:DWORD src1_sel:BYTE_0
	v_and_b32_e32 v10, 32, v9
	v_bfe_i32 v9, v4, 0, 16
	v_add_lshl_u32 v4, v10, v9, 1
	v_lshl_add_u32 v180, v7, 12, v4
	v_lshl_add_u32 v182, v6, 12, v4
	v_bfe_i32 v4, v13, 27, 1
	v_lshrrev_b32_e32 v4, 22, v4
	v_add_u32_e32 v4, v1, v4
	v_and_b32_e32 v4, 0xfffffc00, v4
	v_sub_u32_e32 v1, v1, v4
	v_lshrrev_b32_e32 v4, 4, v1
	v_ashrrev_i32_e32 v5, 31, v13
	v_bitop3_b32 v1, v4, v1, 32 bitop3:0x6c
	v_lshrrev_b32_e32 v5, 26, v5
	v_ashrrev_i32_e32 v4, 31, v1
	v_add_u32_e32 v5, v13, v5
	v_lshrrev_b32_e32 v4, 26, v4
	v_ashrrev_i32_e32 v11, 6, v5
	v_add_u32_e32 v4, v1, v4
	v_lshlrev_b32_e32 v5, 3, v11
	v_ashrrev_i32_e32 v10, 6, v4
	v_and_b32_e32 v5, -16, v5
	v_add_u32_e32 v5, v10, v5
	v_and_b32_e32 v6, 3, v10
	v_lshrrev_b32_e32 v7, 2, v5
	v_lshlrev_b32_e32 v12, 1, v5
	v_and_b32_e32 v4, 0xc0, v4
	s_ashr_i32 s7, s6, 6
	v_and_or_b32 v6, v5, s0, v6
	v_and_b32_e32 v7, 4, v7
	v_and_b32_e32 v12, 24, v12
	v_sub_u32_e32 v1, v1, v4
	s_ashr_i32 s14, s6, 8
	s_lshl_b32 s15, s7, 10
	v_or3_b32 v6, v6, v7, v12
	v_lshlrev_b32_e32 v7, 5, v11
	v_ashrrev_i16_sdwa v1, v202, sext(v1) dst_sel:DWORD dst_unused:UNUSED_PAD src0_sel:DWORD src1_sel:BYTE_0
	v_readlane_b32 s0, v246, 10
	v_and_b32_e32 v7, 32, v7
	v_bfe_i32 v12, v1, 0, 16
	v_readlane_b32 s1, v246, 11
	s_add_u32 s8, s12, s0
	v_add_lshl_u32 v1, v7, v12, 1
	s_addc_u32 s9, s13, s1
	s_add_i32 s16, s15, 0
	v_lshl_add_u32 v184, v6, 12, v1
	s_add_i32 m0, s16, 0x10000
	v_lshl_add_u32 v186, v5, 12, v1
	global_load_lds_dwordx4 v184, s[8:9]
	s_add_i32 m0, s16, 0x12000
	s_add_u32 s0, s8, 0x80000
	global_load_lds_dwordx4 v180, s[8:9]
	s_addc_u32 s1, s9, 0
	s_add_i32 m0, s16, 0x14000
	s_add_i32 s17, s16, 0x2000
	global_load_lds_dwordx4 v184, s[0:1]
	s_add_i32 m0, s16, 0x16000
	s_add_i32 s18, s16, 0x4000
	global_load_lds_dwordx4 v180, s[0:1]
	v_readlane_b32 s0, v246, 12
	s_mov_b32 m0, s16
	v_readlane_b32 s1, v246, 13
	s_add_i32 s19, s16, 0x6000
	v_mov_b32_e32 v185, v3
	v_mov_b32_e32 v181, v3
	s_cmp_eq_u32 s14, 1
	v_lshl_add_u64 v[4:5], s[8:9], 0, v[184:185]
	global_load_lds_dwordx4 v186, s[0:1]
	s_mov_b32 m0, s17
	v_lshl_add_u64 v[6:7], s[8:9], 0, v[180:181]
	global_load_lds_dwordx4 v182, s[0:1]
	v_readlane_b32 s0, v246, 14
	s_mov_b32 m0, s18
	v_readlane_b32 s1, v246, 15
	s_nop 4
	global_load_lds_dwordx4 v186, s[0:1]
	s_mov_b32 m0, s19
	s_nop 0
	global_load_lds_dwordx4 v182, s[0:1]
	s_cselect_b64 s[0:1], -1, 0
	s_cmp_lg_u32 s14, 1
	s_cbranch_scc1 .LBB0_559
	s_barrier
	s_setprio 1

.LBB0_615:
	s_setprio 0
	v_readlane_b32 s0, v250, 8
	v_readlane_b32 s8, v249, 0
	s_or_b32 s20, s0, 3
	v_readlane_b32 s11, v249, 3
	s_cmp_ge_i32 s20, s11
	v_readlane_b32 s9, v249, 1
	v_readlane_b32 s10, v249, 2
	s_cbranch_scc1 .LBB0_665
	s_waitcnt vmcnt(0)
	v_readlane_b32 s2, v247, 41
	v_readlane_b32 s3, v247, 42
	s_waitcnt vmcnt(0) lgkmcnt(0)
	s_barrier
	s_and_saveexec_b64 s[0:1], s[2:3]
	s_cbranch_execz .LBB0_664
	v_readlane_b32 s6, v249, 45
	s_waitcnt vmcnt(0) expcnt(0) lgkmcnt(0)
	s_nop 0
	v_mov_b32_e32 v1, s6
	ds_read_b32 v4, v1
	ds_read_b32 v2, v1 offset:4
	s_waitcnt lgkmcnt(1)
	v_cmp_ne_u32_e32 vcc, 0, v4
	s_cbranch_vccnz .LBB0_632
	v_readlane_b32 s8, v249, 4
	v_readlane_b32 s9, v249, 5
	s_load_dwordx2 s[6:7], s[8:9], 0x4
	v_readlane_b32 s8, v249, 6
	s_mov_b32 s13, 1
	v_readlane_b32 s9, v249, 7
	s_waitcnt lgkmcnt(0)
	s_mul_i32 s12, s6, s8
	s_mul_i32 s12, s12, s7
	s_branch .LBB0_620

.LBB0_1002:
	s_and_b64 vcc, exec, s[0:1]
	s_cbranch_vccz .LBB0_1021
	v_readlane_b32 s0, v248, 56
	v_mov_b32_e32 v1, v0
	v_readlane_b32 s1, v248, 57
	s_andn2_b64 vcc, exec, s[0:1]
	v_readfirstlane_b32 s6, v1
	s_cbranch_vccnz .LBB0_1021
	s_waitcnt vmcnt(0) lgkmcnt(0)
	v_lshlrev_b32_e32 v6, 4, v1
	v_add_u32_e32 v4, 0x2000, v6
	v_ashrrev_i32_e32 v2, 31, v4
	v_lshrrev_b32_e32 v2, 22, v2
	v_add_u32_e32 v2, v4, v2
	v_ashrrev_i32_e32 v2, 10, v2
	v_mul_i32_i24_e32 v5, 0x400, v2
	v_sub_u32_e32 v4, v4, v5
	v_lshrrev_b32_e32 v5, 4, v4
	v_bitop3_b32 v5, v5, v4, 32 bitop3:0x6c
	v_ashrrev_i32_e32 v4, 31, v5
	v_lshrrev_b32_e32 v4, 26, v4
	v_add_u32_e32 v7, v5, v4
	v_lshlrev_b32_e32 v8, 3, v2
	s_lshl_b64 s[0:1], s[54:55], 23
	v_readlane_b32 s2, v251, 27
	v_ashrrev_i32_e32 v4, 6, v7
	v_and_b32_e32 v8, -16, v8
	s_add_u32 s26, s2, s0
	v_readlane_b32 s0, v251, 28
	v_add_u32_e32 v8, v4, v8
	s_addc_u32 s27, s0, s1
	v_and_b32_e32 v9, 3, v4
	s_mov_b32 s0, 0xfffe0
	v_lshrrev_b32_e32 v10, 2, v8
	v_lshlrev_b32_e32 v11, 1, v8
	v_and_b32_e32 v7, 0xc0, v7
	v_and_or_b32 v9, v8, s0, v9
	v_and_b32_e32 v10, 4, v10
	v_and_b32_e32 v11, 24, v11
	v_sub_u32_e32 v5, v5, v7
	v_or3_b32 v9, v9, v10, v11
	v_lshlrev_b32_e32 v10, 5, v2
	v_ashrrev_i16_sdwa v5, v202, sext(v5) dst_sel:DWORD dst_unused:UNUSED_PAD src0_sel:DWORD src1_sel:BYTE_0
	v_and_b32_e32 v10, 32, v10
	v_bfe_i32 v5, v5, 0, 16
	v_add_lshl_u32 v7, v10, v5, 1
	v_lshl_add_u32 v146, v9, 12, v7
	v_lshl_add_u32 v148, v8, 12, v7
	v_bfe_i32 v7, v1, 27, 1
	v_lshrrev_b32_e32 v7, 22, v7
	v_add_u32_e32 v7, v6, v7
	v_and_b32_e32 v7, 0xfffffc00, v7
	v_sub_u32_e32 v6, v6, v7
	v_lshrrev_b32_e32 v7, 4, v6
	v_bitop3_b32 v8, v7, v6, 32 bitop3:0x6c
	v_ashrrev_i32_e32 v7, 31, v1
	v_lshrrev_b32_e32 v7, 26, v7
	v_ashrrev_i32_e32 v6, 31, v8
	v_add_u32_e32 v7, v1, v7
	v_lshrrev_b32_e32 v6, 26, v6
	v_ashrrev_i32_e32 v7, 6, v7
	v_add_u32_e32 v9, v8, v6
	v_lshlrev_b32_e32 v10, 3, v7
	v_ashrrev_i32_e32 v6, 6, v9
	v_and_b32_e32 v10, -16, v10
	v_add_u32_e32 v10, v6, v10
	v_and_b32_e32 v11, 3, v6
	v_lshrrev_b32_e32 v12, 2, v10
	v_lshlrev_b32_e32 v13, 1, v10
	v_and_b32_e32 v9, 0xc0, v9
	s_ashr_i32 s7, s6, 6
	v_and_or_b32 v11, v10, s0, v11
	v_and_b32_e32 v12, 4, v12
	v_and_b32_e32 v13, 24, v13
	v_sub_u32_e32 v8, v8, v9
	s_ashr_i32 s8, s6, 8
	s_lshl_b32 s28, s7, 10
	v_or3_b32 v11, v11, v12, v13
	v_lshlrev_b32_e32 v12, 5, v7
	v_ashrrev_i16_sdwa v8, v202, sext(v8) dst_sel:DWORD dst_unused:UNUSED_PAD src0_sel:DWORD src1_sel:BYTE_0
	v_readlane_b32 s0, v247, 56
	v_and_b32_e32 v12, 32, v12
	v_bfe_i32 v8, v8, 0, 16
	v_readlane_b32 s1, v247, 57
	s_add_u32 s18, s26, s0
	v_add_lshl_u32 v9, v12, v8, 1
	s_addc_u32 s19, s27, s1
	s_add_i32 s34, s28, 0
	v_lshl_add_u32 v150, v11, 12, v9
	s_add_i32 m0, s34, 0x10000
	v_lshl_add_u32 v152, v10, 12, v9
	global_load_lds_dwordx4 v150, s[18:19]
	s_add_i32 m0, s34, 0x12000
	s_add_u32 s0, s18, 0x80000
	global_load_lds_dwordx4 v146, s[18:19]
	s_addc_u32 s1, s19, 0
	s_add_i32 m0, s34, 0x14000
	s_add_i32 s35, s34, 0x2000
	global_load_lds_dwordx4 v150, s[0:1]
	s_add_i32 m0, s34, 0x16000
	s_add_i32 s38, s34, 0x4000
	global_load_lds_dwordx4 v146, s[0:1]
	v_readlane_b32 s0, v247, 58
	s_mov_b32 m0, s34
	v_readlane_b32 s1, v247, 59
	s_add_i32 s39, s34, 0x6000
	s_cmp_eq_u32 s8, 1
	s_nop 2
	global_load_lds_dwordx4 v152, s[0:1]
	s_mov_b32 m0, s35
	s_nop 0
	global_load_lds_dwordx4 v148, s[0:1]
	v_readlane_b32 s0, v247, 60
	s_mov_b32 m0, s38
	v_readlane_b32 s1, v247, 61
	s_nop 4
	global_load_lds_dwordx4 v152, s[0:1]
	s_mov_b32 m0, s39
	s_nop 0
	global_load_lds_dwordx4 v148, s[0:1]
	s_cselect_b64 s[0:1], -1, 0
	s_cmp_lg_u32 s8, 1
	s_cbranch_scc1 .LBB0_1006
	s_barrier
	s_setprio 1

.LBB0_1021:
	s_setprio 0
	v_readlane_b32 s0, v250, 8
	v_readlane_b32 s8, v249, 0
	s_or_b32 s20, s0, 5
	v_readlane_b32 s11, v249, 3
	s_cmp_ge_i32 s20, s11
	v_readlane_b32 s9, v249, 1
	v_readlane_b32 s10, v249, 2
	s_cbranch_scc1 .LBB0_1071
	s_waitcnt vmcnt(0)
	v_readlane_b32 s2, v247, 41
	v_readlane_b32 s3, v247, 42
	s_waitcnt vmcnt(0) lgkmcnt(0)
	s_barrier
	s_and_saveexec_b64 s[0:1], s[2:3]
	s_cbranch_execz .LBB0_1070
	v_readlane_b32 s6, v249, 45
	s_waitcnt vmcnt(0) expcnt(0) lgkmcnt(0)
	s_nop 0
	v_mov_b32_e32 v1, s6
	ds_read_b32 v4, v1
	ds_read_b32 v2, v1 offset:4
	s_waitcnt lgkmcnt(1)
	v_cmp_ne_u32_e32 vcc, 0, v4
	s_cbranch_vccnz .LBB0_1038
	v_readlane_b32 s8, v249, 4
	v_readlane_b32 s9, v249, 5
	s_load_dwordx2 s[6:7], s[8:9], 0x4
	v_readlane_b32 s8, v249, 6
	s_mov_b32 s13, 1
	v_readlane_b32 s9, v249, 7
	s_waitcnt lgkmcnt(0)
	s_mul_i32 s12, s6, s8
	s_mul_i32 s12, s12, s7
	s_branch .LBB0_1026

.LBB0_1073:
	s_andn2_b64 vcc, exec, s[0:1]
	v_readlane_b32 s0, v248, 60
	v_readlane_b32 s1, v248, 61
	s_nop 1
	v_cndmask_b32_e64 v1, 0, 1, s[0:1]
	v_cmp_ne_u32_e64 s[36:37], 1, v1
	s_cbranch_vccnz .LBB0_1144
	v_mov_b32_e32 v1, v0
	s_and_b64 vcc, exec, s[36:37]
	v_readfirstlane_b32 s6, v1
	s_cbranch_vccnz .LBB0_1094
	s_waitcnt vmcnt(0) lgkmcnt(0)
	v_lshlrev_b32_e32 v6, 4, v1
	v_add_u32_e32 v4, 0x2000, v6
	v_ashrrev_i32_e32 v2, 31, v4
	v_lshrrev_b32_e32 v2, 22, v2
	v_add_u32_e32 v2, v4, v2
	v_ashrrev_i32_e32 v2, 10, v2
	v_mul_i32_i24_e32 v5, 0x400, v2
	v_sub_u32_e32 v4, v4, v5
	v_lshrrev_b32_e32 v5, 4, v4
	v_bitop3_b32 v5, v5, v4, 32 bitop3:0x6c
	v_ashrrev_i32_e32 v4, 31, v5
	v_lshrrev_b32_e32 v4, 26, v4
	v_add_u32_e32 v7, v5, v4
	v_lshlrev_b32_e32 v8, 3, v2
	s_lshl_b64 s[0:1], s[54:55], 23
	v_readlane_b32 s2, v251, 25
	v_ashrrev_i32_e32 v4, 6, v7
	v_and_b32_e32 v8, -16, v8
	s_add_u32 s26, s2, s0
	v_readlane_b32 s0, v251, 26
	v_add_u32_e32 v8, v4, v8
	s_addc_u32 s27, s0, s1
	v_and_b32_e32 v9, 3, v4
	s_mov_b32 s0, 0xfffe0
	v_lshrrev_b32_e32 v10, 2, v8
	v_lshlrev_b32_e32 v11, 1, v8
	v_and_b32_e32 v7, 0xc0, v7
	v_and_or_b32 v9, v8, s0, v9
	v_and_b32_e32 v10, 4, v10
	v_and_b32_e32 v11, 24, v11
	v_sub_u32_e32 v5, v5, v7
	v_or3_b32 v9, v9, v10, v11
	v_lshlrev_b32_e32 v10, 5, v2
	v_ashrrev_i16_sdwa v5, v202, sext(v5) dst_sel:DWORD dst_unused:UNUSED_PAD src0_sel:DWORD src1_sel:BYTE_0
	v_and_b32_e32 v10, 32, v10
	v_bfe_i32 v5, v5, 0, 16
	v_add_lshl_u32 v7, v10, v5, 1
	v_lshl_add_u32 v132, v9, 12, v7
	v_lshl_add_u32 v134, v8, 12, v7
	v_bfe_i32 v7, v1, 27, 1
	v_lshrrev_b32_e32 v7, 22, v7
	v_add_u32_e32 v7, v6, v7
	v_and_b32_e32 v7, 0xfffffc00, v7
	v_sub_u32_e32 v6, v6, v7
	v_lshrrev_b32_e32 v7, 4, v6
	v_bitop3_b32 v8, v7, v6, 32 bitop3:0x6c
	v_ashrrev_i32_e32 v7, 31, v1
	v_lshrrev_b32_e32 v7, 26, v7
	v_ashrrev_i32_e32 v6, 31, v8
	v_add_u32_e32 v7, v1, v7
	v_lshrrev_b32_e32 v6, 26, v6
	v_ashrrev_i32_e32 v7, 6, v7
	v_add_u32_e32 v9, v8, v6
	v_lshlrev_b32_e32 v10, 3, v7
	v_ashrrev_i32_e32 v6, 6, v9
	v_and_b32_e32 v10, -16, v10
	v_add_u32_e32 v10, v6, v10
	v_and_b32_e32 v11, 3, v6
	v_lshrrev_b32_e32 v12, 2, v10
	v_lshlrev_b32_e32 v13, 1, v10
	v_and_b32_e32 v9, 0xc0, v9
	s_ashr_i32 s7, s6, 6
	v_and_or_b32 v11, v10, s0, v11
	v_and_b32_e32 v12, 4, v12
	v_and_b32_e32 v13, 24, v13
	v_sub_u32_e32 v8, v8, v9
	s_ashr_i32 s8, s6, 8
	s_lshl_b32 s28, s7, 10
	v_or3_b32 v11, v11, v12, v13
	v_lshlrev_b32_e32 v12, 5, v7
	v_ashrrev_i16_sdwa v8, v202, sext(v8) dst_sel:DWORD dst_unused:UNUSED_PAD src0_sel:DWORD src1_sel:BYTE_0
	v_readlane_b32 s0, v246, 17
	v_and_b32_e32 v12, 32, v12
	v_bfe_i32 v8, v8, 0, 16
	v_readlane_b32 s1, v246, 18
	s_add_u32 s20, s26, s0
	v_add_lshl_u32 v9, v12, v8, 1
	s_addc_u32 s21, s27, s1
	s_add_i32 s34, s28, 0
	v_lshl_add_u32 v136, v11, 12, v9
	s_add_i32 m0, s34, 0x10000
	v_lshl_add_u32 v138, v10, 12, v9
	global_load_lds_dwordx4 v136, s[20:21]
	s_add_i32 m0, s34, 0x12000
	s_add_u32 s0, s20, 0x80000
	global_load_lds_dwordx4 v132, s[20:21]
	s_addc_u32 s1, s21, 0
	s_add_i32 m0, s34, 0x14000
	s_add_i32 s35, s34, 0x2000
	global_load_lds_dwordx4 v136, s[0:1]
	s_add_i32 m0, s34, 0x16000
	s_add_i32 s40, s34, 0x4000
	global_load_lds_dwordx4 v132, s[0:1]
	v_readlane_b32 s0, v246, 21
	s_mov_b32 m0, s34
	v_readlane_b32 s1, v246, 22
	s_add_i32 s41, s34, 0x6000
	s_cmp_eq_u32 s8, 1
	s_nop 2
	global_load_lds_dwordx4 v138, s[0:1]
	s_mov_b32 m0, s35
	s_nop 0
	global_load_lds_dwordx4 v134, s[0:1]
	v_readlane_b32 s0, v246, 23
	s_mov_b32 m0, s40
	v_readlane_b32 s1, v246, 24
	s_nop 4
	global_load_lds_dwordx4 v138, s[0:1]
	s_mov_b32 m0, s41
	s_nop 0
	global_load_lds_dwordx4 v134, s[0:1]
	s_cselect_b64 s[0:1], -1, 0
	s_cmp_lg_u32 s8, 1
	s_cbranch_scc1 .LBB0_1077
	s_barrier
	s_setprio 1

.LBB0_1094:
	s_setprio 0
	v_readlane_b32 s0, v250, 8
	v_readlane_b32 s8, v249, 0
	s_or_b32 s20, s0, 6
	v_readlane_b32 s11, v249, 3
	s_cmp_ge_i32 s20, s11
	v_readlane_b32 s9, v249, 1
	v_readlane_b32 s10, v249, 2
	s_cbranch_scc1 .LBB0_1144
	s_waitcnt vmcnt(0)
	v_readlane_b32 s2, v247, 41
	v_readlane_b32 s3, v247, 42
	s_waitcnt vmcnt(0) lgkmcnt(0)
	s_barrier
	s_and_saveexec_b64 s[0:1], s[2:3]
	s_cbranch_execz .LBB0_1143
	v_readlane_b32 s6, v249, 45
	s_waitcnt vmcnt(0) expcnt(0) lgkmcnt(0)
	s_nop 0
	v_mov_b32_e32 v1, s6
	ds_read_b32 v4, v1
	ds_read_b32 v2, v1 offset:4
	s_waitcnt lgkmcnt(1)
	v_cmp_ne_u32_e32 vcc, 0, v4
	s_cbranch_vccnz .LBB0_1111
	v_readlane_b32 s8, v249, 4
	v_readlane_b32 s9, v249, 5
	s_load_dwordx2 s[6:7], s[8:9], 0x4
	v_readlane_b32 s8, v249, 6
	s_mov_b32 s13, 1
	v_readlane_b32 s9, v249, 7
	s_waitcnt lgkmcnt(0)
	s_mul_i32 s12, s6, s8
	s_mul_i32 s12, s12, s7
	s_branch .LBB0_1099

.LBB0_1212:
	s_andn2_b64 vcc, exec, s[6:7]
	s_cbranch_vccnz .LBB0_1279
	v_readlane_b32 s2, v247, 38
	s_waitcnt vmcnt(0)
	v_mov_b32_e32 v10, v0
	v_readlane_b32 s3, v247, 39
	s_andn2_b64 vcc, exec, s[2:3]
	v_readfirstlane_b32 s8, v10
	s_cbranch_vccnz .LBB0_1229
	v_lshlrev_b32_e32 v1, 4, v10
	v_add_u32_e32 v2, 0x2000, v1
	v_ashrrev_i32_e32 v4, 31, v2
	v_lshrrev_b32_e32 v4, 22, v4
	v_add_u32_e32 v4, v2, v4
	v_ashrrev_i32_e32 v4, 10, v4
	v_mul_i32_i24_e32 v5, 0x400, v4
	v_sub_u32_e32 v2, v2, v5
	v_lshrrev_b32_e32 v5, 4, v2
	v_bitop3_b32 v2, v5, v2, 32 bitop3:0x6c
	v_ashrrev_i32_e32 v5, 31, v2
	v_lshrrev_b32_e32 v5, 26, v5
	s_waitcnt lgkmcnt(1)
	v_add_u32_e32 v6, v2, v5
	s_waitcnt lgkmcnt(0)
	v_lshlrev_b32_e32 v7, 3, v4
	s_lshl_b64 s[6:7], s[54:55], 25
	v_readlane_b32 s2, v251, 23
	v_ashrrev_i32_e32 v5, 6, v6
	v_and_b32_e32 v7, -16, v7
	s_add_u32 s26, s2, s6
	v_readlane_b32 s2, v251, 24
	v_add_u32_e32 v7, v5, v7
	s_addc_u32 s27, s2, s7
	v_and_b32_e32 v8, 3, v5
	s_mov_b32 s2, 0xfffe0
	v_lshrrev_b32_e32 v9, 2, v7
	v_lshlrev_b32_e32 v11, 1, v7
	v_and_b32_e32 v6, 0xc0, v6
	v_and_or_b32 v8, v7, s2, v8
	v_and_b32_e32 v9, 4, v9
	v_and_b32_e32 v11, 24, v11
	v_sub_u32_e32 v2, v2, v6
	v_or3_b32 v8, v8, v9, v11
	v_lshlrev_b32_e32 v9, 5, v4
	v_ashrrev_i16_sdwa v2, v202, sext(v2) dst_sel:DWORD dst_unused:UNUSED_PAD src0_sel:DWORD src1_sel:BYTE_0
	v_and_b32_e32 v9, 32, v9
	v_bfe_i32 v6, v2, 0, 16
	v_add_lshl_u32 v2, v9, v6, 1
	v_lshl_add_u32 v132, v8, 12, v2
	v_lshl_add_u32 v134, v7, 12, v2
	v_bfe_i32 v2, v10, 27, 1
	v_lshrrev_b32_e32 v2, 22, v2
	v_add_u32_e32 v2, v1, v2
	v_and_b32_e32 v2, 0xfffffc00, v2
	v_sub_u32_e32 v1, v1, v2
	v_lshrrev_b32_e32 v2, 4, v1
	v_ashrrev_i32_e32 v8, 31, v10
	v_bitop3_b32 v1, v2, v1, 32 bitop3:0x6c
	v_lshrrev_b32_e32 v8, 26, v8
	v_ashrrev_i32_e32 v2, 31, v1
	v_add_u32_e32 v8, v10, v8
	v_lshrrev_b32_e32 v2, 26, v2
	v_ashrrev_i32_e32 v8, 6, v8
	v_add_u32_e32 v2, v1, v2
	v_lshlrev_b32_e32 v9, 3, v8
	v_ashrrev_i32_e32 v7, 6, v2
	v_and_b32_e32 v9, -16, v9
	v_add_u32_e32 v11, v7, v9
	v_and_b32_e32 v9, 3, v7
	v_lshrrev_b32_e32 v12, 2, v11
	v_lshlrev_b32_e32 v13, 1, v11
	v_and_b32_e32 v2, 0xc0, v2
	s_ashr_i32 s9, s8, 6
	v_and_or_b32 v9, v11, s2, v9
	v_and_b32_e32 v12, 4, v12
	v_and_b32_e32 v13, 24, v13
	v_sub_u32_e32 v1, v1, v2
	s_ashr_i32 s10, s8, 8
	s_lshl_b32 s28, s9, 10
	v_or3_b32 v12, v9, v12, v13
	v_lshlrev_b32_e32 v9, 5, v8
	v_ashrrev_i16_sdwa v1, v202, sext(v1) dst_sel:DWORD dst_unused:UNUSED_PAD src0_sel:DWORD src1_sel:BYTE_0
	v_readlane_b32 s2, v246, 2
	v_and_b32_e32 v13, 32, v9
	v_bfe_i32 v9, v1, 0, 16
	v_readlane_b32 s3, v246, 3
	s_add_u32 s20, s26, s2
	v_add_lshl_u32 v1, v13, v9, 1
	s_addc_u32 s21, s27, s3
	s_add_i32 s34, s28, 0
	v_lshl_add_u32 v2, v12, 12, v1
	s_add_i32 m0, s34, 0x10000
	v_readlane_b32 s2, v246, 4
	global_load_lds_dwordx4 v2, s[20:21]
	s_add_i32 m0, s34, 0x12000
	s_add_u32 s6, s20, 0x80000
	global_load_lds_dwordx4 v132, s[20:21]
	s_addc_u32 s7, s21, 0
	s_add_i32 m0, s34, 0x14000
	v_lshl_add_u32 v136, v11, 12, v1
	global_load_lds_dwordx4 v2, s[6:7]
	s_add_i32 m0, s34, 0x16000
	v_readlane_b32 s3, v246, 5
	global_load_lds_dwordx4 v132, s[6:7]
	s_mov_b32 m0, s34
	s_add_i32 s35, s34, 0x2000
	s_add_i32 s42, s34, 0x4000
	s_nop 0
	global_load_lds_dwordx4 v136, s[2:3]
	s_mov_b32 m0, s35
	s_add_i32 s43, s34, 0x6000
	global_load_lds_dwordx4 v134, s[2:3]
	v_readlane_b32 s2, v246, 6
	s_mov_b32 m0, s42
	v_readlane_b32 s3, v246, 7
	s_cmp_eq_u32 s10, 1
	s_cselect_b64 s[6:7], -1, 0
	s_cmp_lg_u32 s10, 1
	s_nop 1
	global_load_lds_dwordx4 v136, s[2:3]
	s_mov_b32 m0, s43
	s_nop 0
	global_load_lds_dwordx4 v134, s[2:3]
	s_cbranch_scc1 .LBB0_1216
	s_barrier
	s_setprio 1

.LBB0_1229:
	s_setprio 0
	v_readlane_b32 s2, v250, 8
	v_readlane_b32 s8, v249, 0
	s_add_i32 s24, s2, 8
	v_readlane_b32 s11, v249, 3
	s_cmp_ge_i32 s24, s11
	v_readlane_b32 s9, v249, 1
	v_readlane_b32 s10, v249, 2
	s_cbranch_scc1 .LBB0_1279
	s_waitcnt vmcnt(0)
	v_readlane_b32 s2, v247, 41
	v_readlane_b32 s3, v247, 42
	s_waitcnt vmcnt(0) lgkmcnt(0)
	s_barrier
	s_and_saveexec_b64 s[6:7], s[2:3]
	s_cbranch_execz .LBB0_1278
	v_readlane_b32 s8, v249, 45
	s_waitcnt vmcnt(0) expcnt(0) lgkmcnt(0)
	s_nop 0
	v_mov_b32_e32 v1, s8
	ds_read_b32 v4, v1
	ds_read_b32 v2, v1 offset:4
	s_waitcnt lgkmcnt(1)
	v_cmp_ne_u32_e32 vcc, 0, v4
	s_cbranch_vccnz .LBB0_1246
	v_readlane_b32 s10, v249, 4
	v_readlane_b32 s11, v249, 5
	s_load_dwordx2 s[8:9], s[10:11], 0x4
	v_readlane_b32 s10, v249, 6
	s_mov_b32 s15, 1
	v_readlane_b32 s11, v249, 7
	s_waitcnt lgkmcnt(0)
	s_mul_i32 s14, s8, s10
	s_mul_i32 s14, s14, s9
	s_branch .LBB0_1234

.LBB0_1281:
	s_andn2_b64 vcc, exec, s[6:7]
	s_cbranch_vccnz .LBB0_1352
	v_mov_b32_e32 v1, v0
	s_and_b64 vcc, exec, s[36:37]
	v_readfirstlane_b32 s8, v1
	s_cbranch_vccnz .LBB0_1302
	s_waitcnt vmcnt(0)
	v_lshlrev_b32_e32 v4, 4, v1
	v_add_u32_e32 v5, 0x2000, v4
	v_ashrrev_i32_e32 v2, 31, v5
	v_lshrrev_b32_e32 v2, 22, v2
	v_add_u32_e32 v2, v5, v2
	v_ashrrev_i32_e32 v2, 10, v2
	s_waitcnt lgkmcnt(1)
	v_mul_i32_i24_e32 v6, 0x400, v2
	v_sub_u32_e32 v5, v5, v6
	v_lshrrev_b32_e32 v6, 4, v5
	v_bitop3_b32 v5, v6, v5, 32 bitop3:0x6c
	v_ashrrev_i32_e32 v6, 31, v5
	v_lshrrev_b32_e32 v6, 26, v6
	v_add_u32_e32 v6, v5, v6
	s_waitcnt lgkmcnt(0)
	v_lshlrev_b32_e32 v7, 3, v2
	s_lshl_b64 s[6:7], s[54:55], 25
	v_readlane_b32 s2, v248, 46
	v_ashrrev_i32_e32 v8, 6, v6
	v_and_b32_e32 v7, -16, v7
	s_add_u32 s28, s2, s6
	v_readlane_b32 s2, v248, 47
	v_add_u32_e32 v7, v8, v7
	s_addc_u32 s34, s2, s7
	v_and_b32_e32 v9, 3, v8
	s_mov_b32 s2, 0x3ffe0
	v_lshrrev_b32_e32 v10, 2, v7
	v_lshlrev_b32_e32 v11, 1, v7
	v_and_b32_e32 v6, 0xc0, v6
	v_and_or_b32 v9, v7, s2, v9
	v_and_b32_e32 v10, 4, v10
	v_and_b32_e32 v11, 24, v11
	v_sub_u32_e32 v5, v5, v6
	v_or3_b32 v10, v9, v10, v11
	v_lshlrev_b32_e32 v9, 5, v2
	v_ashrrev_i16_sdwa v5, v202, sext(v5) dst_sel:DWORD dst_unused:UNUSED_PAD src0_sel:DWORD src1_sel:BYTE_0
	v_and_b32_e32 v11, 32, v9
	v_bfe_i32 v9, v5, 0, 16
	v_add_lshl_u32 v5, v11, v9, 1
	v_lshl_add_u32 v132, v10, 14, v5
	v_lshl_add_u32 v134, v7, 14, v5
	v_bfe_i32 v5, v1, 27, 1
	v_lshrrev_b32_e32 v5, 22, v5
	v_add_u32_e32 v5, v4, v5
	v_and_b32_e32 v5, 0xfffffc00, v5
	v_sub_u32_e32 v4, v4, v5
	v_lshrrev_b32_e32 v5, 4, v4
	v_ashrrev_i32_e32 v6, 31, v1
	v_bitop3_b32 v4, v5, v4, 32 bitop3:0x6c
	v_lshrrev_b32_e32 v6, 26, v6
	v_ashrrev_i32_e32 v5, 31, v4
	v_add_u32_e32 v6, v1, v6
	v_lshrrev_b32_e32 v5, 26, v5
	v_ashrrev_i32_e32 v11, 6, v6
	v_add_u32_e32 v5, v4, v5
	v_lshlrev_b32_e32 v6, 3, v11
	v_ashrrev_i32_e32 v10, 6, v5
	v_and_b32_e32 v6, -16, v6
	v_add_u32_e32 v6, v10, v6
	v_and_b32_e32 v7, 3, v10
	v_lshrrev_b32_e32 v12, 2, v6
	v_lshlrev_b32_e32 v13, 1, v6
	v_and_b32_e32 v5, 0xc0, v5
	s_ashr_i32 s9, s8, 6
	v_and_or_b32 v7, v6, s2, v7
	v_and_b32_e32 v12, 4, v12
	v_and_b32_e32 v13, 24, v13
	v_sub_u32_e32 v4, v4, v5
	s_ashr_i32 s10, s8, 8
	s_lshl_b32 s35, s9, 10
	v_or3_b32 v7, v7, v12, v13
	v_lshlrev_b32_e32 v12, 5, v11
	v_ashrrev_i16_sdwa v4, v202, sext(v4) dst_sel:DWORD dst_unused:UNUSED_PAD src0_sel:DWORD src1_sel:BYTE_0
	v_readlane_b32 s2, v246, 27
	v_and_b32_e32 v13, 32, v12
	v_bfe_i32 v12, v4, 0, 16
	v_readlane_b32 s3, v246, 28
	s_add_u32 s24, s28, s2
	v_add_lshl_u32 v4, v13, v12, 1
	s_addc_u32 s25, s34, s3
	s_add_i32 s40, s35, 0
	v_lshl_add_u32 v136, v7, 14, v4
	s_add_i32 m0, s40, 0x10000
	v_readlane_b32 s2, v246, 31
	global_load_lds_dwordx4 v136, s[24:25]
	s_add_i32 m0, s40, 0x12000
	s_add_u32 s6, s24, 0x200000
	global_load_lds_dwordx4 v132, s[24:25]
	s_addc_u32 s7, s25, 0
	s_add_i32 m0, s40, 0x14000
	v_lshl_add_u32 v138, v6, 14, v4
	global_load_lds_dwordx4 v136, s[6:7]
	s_add_i32 m0, s40, 0x16000
	v_readlane_b32 s3, v246, 32
	global_load_lds_dwordx4 v132, s[6:7]
	s_mov_b32 m0, s40
	s_add_i32 s41, s40, 0x2000
	s_add_i32 s42, s40, 0x4000
	s_nop 0
	global_load_lds_dwordx4 v138, s[2:3]
	s_mov_b32 m0, s41
	s_add_i32 s43, s40, 0x6000
	global_load_lds_dwordx4 v134, s[2:3]
	v_readlane_b32 s2, v246, 33
	s_mov_b32 m0, s42
	v_readlane_b32 s3, v246, 34
	v_mov_b32_e32 v137, v3
	v_mov_b32_e32 v133, v3
	s_cmp_eq_u32 s10, 1
	v_lshl_add_u64 v[4:5], s[24:25], 0, v[136:137]
	s_cselect_b64 s[6:7], -1, 0
	global_load_lds_dwordx4 v138, s[2:3]
	s_mov_b32 m0, s43
	s_cmp_lg_u32 s10, 1
	global_load_lds_dwordx4 v134, s[2:3]
	v_lshl_add_u64 v[6:7], s[24:25], 0, v[132:133]
	s_cbranch_scc1 .LBB0_1285
	s_barrier
	s_setprio 1

.LBB0_1302:
	s_setprio 0
	v_readlane_b32 s2, v250, 8
	v_readlane_b32 s8, v249, 0
	s_add_i32 s24, s2, 9
	v_readlane_b32 s11, v249, 3
	s_cmp_ge_i32 s24, s11
	v_readlane_b32 s9, v249, 1
	v_readlane_b32 s10, v249, 2
	s_cbranch_scc1 .LBB0_1352
	s_waitcnt vmcnt(0)
	v_readlane_b32 s2, v247, 41
	v_readlane_b32 s3, v247, 42
	s_waitcnt vmcnt(0) lgkmcnt(0)
	s_barrier
	s_and_saveexec_b64 s[6:7], s[2:3]
	s_cbranch_execz .LBB0_1351
	v_readlane_b32 s8, v249, 45
	s_waitcnt vmcnt(0) expcnt(0) lgkmcnt(0)
	s_nop 0
	v_mov_b32_e32 v1, s8
	ds_read_b32 v4, v1
	ds_read_b32 v2, v1 offset:4
	s_waitcnt lgkmcnt(1)
	v_cmp_ne_u32_e32 vcc, 0, v4
	s_cbranch_vccnz .LBB0_1319
	v_readlane_b32 s10, v249, 4
	v_readlane_b32 s11, v249, 5
	s_load_dwordx2 s[8:9], s[10:11], 0x4
	v_readlane_b32 s10, v249, 6
	s_mov_b32 s15, 1
	v_readlane_b32 s11, v249, 7
	s_waitcnt lgkmcnt(0)
	s_mul_i32 s14, s8, s10
	s_mul_i32 s14, s14, s9
	s_branch .LBB0_1307
